# out-proj epilogue software-pipelined: 3 x-buffers, saddr loads/stores, counted vmcnt instead of 4 serial vmcnt(0) batches
# speedup vs baseline: 1.0173x; 1.0040x over previous
; #define PG8_STAGE(bufoff, gbase, voff) do { _Pragma("unroll") for (int _i = 0; _i < 2; ++_i) \
;     __builtin_amdgcn_global_load_lds((const unsigned*)((const char*)(gbase) + (voff)[_i]), (LAS unsigned*)(lds + (bufoff) + ldsw + _i * 8192), 16, 0, 0); } while (0)
; #define PG8_LDA(dst, b, h) do { _Pragma("unroll") for (int m = 0; m < 4; ++m) _Pragma("unroll") for (int k = 0; k < 2; ++k) dst[m][k] = *(const LAS bf16x8*)(lds + PG8_SA(b, h) + aoff + m * 2048 + k * 1024); } while (0)
; #define PG8_LDB(dst, b, h) do { _Pragma("unroll") for (int n = 0; n < 2; ++n) _Pragma("unroll") for (int k = 0; k < 2; ++k) dst[n][k] = *(const LAS bf16x8*)(lds + PG8_SB(b, h) + boff + n * 2048 + k * 1024); } while (0)
; #define PG8_MMA(ai, bj, At, Bt) do { __builtin_amdgcn_s_setprio(1); _Pragma("unroll") for (int m = 0; m < 4; ++m) _Pragma("unroll") for (int n = 0; n < 2; ++n) _Pragma("unroll") for (int k = 0; k < 2; ++k) \
;     acc[ai][bj][m][n] = __builtin_amdgcn_mfma_f32_16x16x32_bf16(Bt[n][k], At[m][k], acc[ai][bj][m][n], 0, 0, 0); __builtin_amdgcn_s_setprio(0); } while (0)
; #define PG8_WAIT_L(n) asm volatile("s_waitcnt lgkmcnt(" #n ")" ::: "memory")
; #define PG8_BAR __builtin_amdgcn_s_barrier()
; #define PG8_SCHED __builtin_amdgcn_sched_barrier(0)
; template <class Epi, class Sched>
; DI void gemm_phase(LAS unsigned char* lds, const Sched& S, const Epi& E) {
;     ...
;       PG8_LDB(B0, 0, 0); PG8_SCHED; PG8_LDA(At, 0, 0); PG8_STAGE(PG8_SA(1, 1), a1 + hstep, voffA);
;       PG8_WAIT_L(8); PG8_BAR; PG8_WAIT_L(0); PG8_MMA(0, 0, At, B0); PG8_BAR; PG8_SCHED;
;       PG8_LDB(B1, 0, 1); PG8_STAGE(PG8_SB(0, 0), b2, voffB);
;       PG8_BAR; PG8_WAIT_L(0); PG8_MMA(0, 1, At, B1); PG8_BAR;
;       PG8_LDA(At, 0, 1); PG8_STAGE(PG8_SA(0, 0), a2, voffA);
;       PG8_BAR; PG8_WAIT_L(0); PG8_MMA(1, 0, At, B0); PG8_BAR; PG8_SCHED;
.LBB0_618:
	ds_read_b128 v[128:131], v173
	ds_read_b128 v[132:135], v173 offset:1024
	ds_read_b128 v[136:139], v173 offset:2048
	ds_read_b128 v[140:143], v173 offset:3072
	s_add_u32 s36, s30, 0xfff80080
	s_addc_u32 s37, s31, -1
	s_cmp_eq_u32 s65, 28
	s_cselect_b32 s39, s17, s37
	s_cselect_b32 s38, s16, s36
	s_cselect_b32 s37, s21, s25
	s_cselect_b32 s36, s20, s13
	v_lshl_add_u64 v[158:159], s[30:31], 0, v[154:155]
	s_add_i32 m0, s11, 0xc000
	ds_read_b128 v[162:165], v174
	ds_read_b128 v[166:169], v174 offset:1024
	ds_read_b128 v[176:179], v174 offset:2048
	ds_read_b128 v[180:183], v174 offset:3072
	ds_read_b128 v[184:187], v174 offset:4096
	ds_read_b128 v[188:191], v174 offset:5120
	ds_read_b128 v[192:195], v174 offset:6144
	ds_read_b128 v[196:199], v174 offset:7168
	global_load_lds_dwordx4 v[158:159], off
	v_lshl_add_u64 v[158:159], s[30:31], 0, v[156:157]
	s_add_i32 m0, s11, 0xe000
	s_nop 0
	global_load_lds_dwordx4 v[158:159], off
	s_waitcnt lgkmcnt(8)
	s_barrier
	s_waitcnt lgkmcnt(0)
	s_setprio 1
	s_waitcnt lgkmcnt(0)
	v_mfma_f32_16x16x32_bf16 v[124:127], v[128:131], v[162:165], v[124:127]
	v_mfma_f32_16x16x32_bf16 v[120:123], v[136:139], v[162:165], v[120:123]
	v_mfma_f32_16x16x32_bf16 v[108:111], v[128:131], v[176:179], v[108:111]
	v_mfma_f32_16x16x32_bf16 v[104:107], v[136:139], v[176:179], v[104:107]
	v_mfma_f32_16x16x32_bf16 v[92:95], v[128:131], v[184:187], v[92:95]
	v_mfma_f32_16x16x32_bf16 v[88:91], v[136:139], v[184:187], v[88:91]
	v_mfma_f32_16x16x32_bf16 v[84:87], v[128:131], v[192:195], v[84:87]
	v_mfma_f32_16x16x32_bf16 v[80:83], v[136:139], v[192:195], v[80:83]
	v_mfma_f32_16x16x32_bf16 v[124:127], v[132:135], v[166:169], v[124:127]
	v_mfma_f32_16x16x32_bf16 v[120:123], v[140:143], v[166:169], v[120:123]
	v_mfma_f32_16x16x32_bf16 v[108:111], v[132:135], v[180:183], v[108:111]
	v_mfma_f32_16x16x32_bf16 v[104:107], v[140:143], v[180:183], v[104:107]
	v_mfma_f32_16x16x32_bf16 v[92:95], v[132:135], v[188:191], v[92:95]
	v_mfma_f32_16x16x32_bf16 v[88:91], v[140:143], v[188:191], v[88:91]
	v_mfma_f32_16x16x32_bf16 v[84:87], v[132:135], v[196:199], v[84:87]
	v_mfma_f32_16x16x32_bf16 v[80:83], v[140:143], v[196:199], v[80:83]
	s_setprio 0
	s_barrier
	s_add_i32 s66, s56, s3
	v_lshl_add_u64 v[158:159], s[36:37], 0, v[146:147]
	s_mov_b32 m0, s66
	ds_read_b128 v[200:203], v175
	ds_read_b128 v[204:207], v175 offset:1024
	ds_read_b128 v[208:211], v175 offset:2048
	ds_read_b128 v[212:215], v175 offset:3072
	global_load_lds_dwordx4 v[158:159], off
	v_lshl_add_u64 v[216:217], s[36:37], 0, v[150:151]
	s_add_i32 m0, s66, 0x2000
	s_nop 0
	global_load_lds_dwordx4 v[216:217], off
	s_barrier
	s_waitcnt lgkmcnt(0)
	s_setprio 1
	s_waitcnt lgkmcnt(0)
	v_mfma_f32_16x16x32_bf16 v[116:119], v[200:203], v[162:165], v[116:119]
	v_mfma_f32_16x16x32_bf16 v[112:115], v[208:211], v[162:165], v[112:115]
	v_mfma_f32_16x16x32_bf16 v[100:103], v[200:203], v[176:179], v[100:103]
	v_mfma_f32_16x16x32_bf16 v[96:99], v[208:211], v[176:179], v[96:99]
	v_mfma_f32_16x16x32_bf16 v[76:79], v[200:203], v[184:187], v[76:79]
	v_mfma_f32_16x16x32_bf16 v[72:75], v[208:211], v[184:187], v[72:75]
	v_mfma_f32_16x16x32_bf16 v[68:71], v[200:203], v[192:195], v[68:71]
	v_mfma_f32_16x16x32_bf16 v[64:67], v[208:211], v[192:195], v[64:67]
	v_mfma_f32_16x16x32_bf16 v[116:119], v[204:207], v[166:169], v[116:119]
	v_mfma_f32_16x16x32_bf16 v[112:115], v[212:215], v[166:169], v[112:115]
	v_mfma_f32_16x16x32_bf16 v[100:103], v[204:207], v[180:183], v[100:103]
	v_mfma_f32_16x16x32_bf16 v[96:99], v[212:215], v[180:183], v[96:99]
	v_mfma_f32_16x16x32_bf16 v[76:79], v[204:207], v[188:191], v[76:79]
	v_mfma_f32_16x16x32_bf16 v[72:75], v[212:215], v[188:191], v[72:75]
	v_mfma_f32_16x16x32_bf16 v[68:71], v[204:207], v[196:199], v[68:71]
	v_mfma_f32_16x16x32_bf16 v[64:67], v[212:215], v[196:199], v[64:67]
	s_setprio 0
	s_mov_b32 m0, s11
	v_lshl_add_u64 v[218:219], s[38:39], 0, v[144:145]
	s_barrier
	ds_read_b128 v[162:165], v174 offset:16384
	ds_read_b128 v[166:169], v174 offset:17408
	ds_read_b128 v[176:179], v174 offset:18432
	ds_read_b128 v[180:183], v174 offset:19456
	ds_read_b128 v[184:187], v174 offset:20480
	ds_read_b128 v[188:191], v174 offset:21504
	ds_read_b128 v[192:195], v174 offset:22528
	ds_read_b128 v[196:199], v174 offset:23552
	global_load_lds_dwordx4 v[218:219], off
	v_lshl_add_u64 v[220:221], s[38:39], 0, v[148:149]
	s_mov_b32 m0, s29
	s_nop 0
	global_load_lds_dwordx4 v[220:221], off
	s_barrier
	s_waitcnt lgkmcnt(0)
	s_setprio 1
	s_waitcnt lgkmcnt(0)
	v_mfma_f32_16x16x32_bf16 v[60:63], v[128:131], v[162:165], v[60:63]
	v_mfma_f32_16x16x32_bf16 v[56:59], v[136:139], v[162:165], v[56:59]
	v_mfma_f32_16x16x32_bf16 v[44:47], v[128:131], v[176:179], v[44:47]
	v_mfma_f32_16x16x32_bf16 v[40:43], v[136:139], v[176:179], v[40:43]
	v_mfma_f32_16x16x32_bf16 v[28:31], v[128:131], v[184:187], v[28:31]
	v_mfma_f32_16x16x32_bf16 v[24:27], v[136:139], v[184:187], v[24:27]
	v_mfma_f32_16x16x32_bf16 v[20:23], v[128:131], v[192:195], v[20:23]
	v_mfma_f32_16x16x32_bf16 v[16:19], v[136:139], v[192:195], v[16:19]
	v_mfma_f32_16x16x32_bf16 v[60:63], v[132:135], v[166:169], v[60:63]
	v_mfma_f32_16x16x32_bf16 v[56:59], v[140:143], v[166:169], v[56:59]
	v_mfma_f32_16x16x32_bf16 v[44:47], v[132:135], v[180:183], v[44:47]
	v_mfma_f32_16x16x32_bf16 v[40:43], v[140:143], v[180:183], v[40:43]
	v_mfma_f32_16x16x32_bf16 v[28:31], v[132:135], v[188:191], v[28:31]
	v_mfma_f32_16x16x32_bf16 v[24:27], v[140:143], v[188:191], v[24:27]
	v_mfma_f32_16x16x32_bf16 v[20:23], v[132:135], v[196:199], v[20:23]
	v_mfma_f32_16x16x32_bf16 v[16:19], v[140:143], v[196:199], v[16:19]
	s_setprio 0
	s_barrier
; #define PG8_STAGE(bufoff, gbase, voff) do { _Pragma("unroll") for (int _i = 0; _i < 2; ++_i) \
;     __builtin_amdgcn_global_load_lds((const unsigned*)((const char*)(gbase) + (voff)[_i]), (LAS unsigned*)(lds + (bufoff) + ldsw + _i * 8192), 16, 0, 0); } while (0)
; #define PG8_LDA(dst, b, h) do { _Pragma("unroll") for (int m = 0; m < 4; ++m) _Pragma("unroll") for (int k = 0; k < 2; ++k) dst[m][k] = *(const LAS bf16x8*)(lds + PG8_SA(b, h) + aoff + m * 2048 + k * 1024); } while (0)
; #define PG8_LDB(dst, b, h) do { _Pragma("unroll") for (int n = 0; n < 2; ++n) _Pragma("unroll") for (int k = 0; k < 2; ++k) dst[n][k] = *(const LAS bf16x8*)(lds + PG8_SB(b, h) + boff + n * 2048 + k * 1024); } while (0)
; #define PG8_MMA(ai, bj, At, Bt) do { __builtin_amdgcn_s_setprio(1); _Pragma("unroll") for (int m = 0; m < 4; ++m) _Pragma("unroll") for (int n = 0; n < 2; ++n) _Pragma("unroll") for (int k = 0; k < 2; ++k) \
;     acc[ai][bj][m][n] = __builtin_amdgcn_mfma_f32_16x16x32_bf16(Bt[n][k], At[m][k], acc[ai][bj][m][n], 0, 0, 0); __builtin_amdgcn_s_setprio(0); } while (0)
; #define PG8_WAIT_V(n) asm volatile("s_waitcnt vmcnt(" #n ")" ::: "memory")
; #define PG8_WAIT_L(n) asm volatile("s_waitcnt lgkmcnt(" #n ")" ::: "memory")
; #define PG8_BAR __builtin_amdgcn_s_barrier()
; #define PG8_SCHED __builtin_amdgcn_sched_barrier(0)
; template <class Epi, class Sched>
; DI void gemm_phase(LAS unsigned char* lds, const Sched& S, const Epi& E) {
;     ...
;       PG8_STAGE(PG8_SB(0, 1), b2 + hstep, voffB);
;       PG8_WAIT_V(6); PG8_BAR; PG8_MMA(1, 1, At, B1); PG8_BAR;
;       PG8_LDB(B0, 1, 0); PG8_SCHED; PG8_LDA(At, 1, 0); PG8_STAGE(PG8_SA(0, 1), a2 + hstep, voffA);
;       PG8_WAIT_L(8); PG8_BAR; PG8_WAIT_L(0); PG8_MMA(0, 0, At, B0); PG8_BAR; PG8_SCHED;
;       PG8_LDB(B1, 1, 1); PG8_STAGE(PG8_SB(1, 0), b3, voffB);
;       PG8_BAR; PG8_WAIT_L(0); PG8_MMA(0, 1, At, B1); PG8_BAR;
;       PG8_LDA(At, 1, 1); PG8_STAGE(PG8_SA(1, 0), a3, voffA);
;       PG8_BAR; PG8_WAIT_L(0); PG8_MMA(1, 0, At, B0); PG8_BAR; PG8_SCHED;
	s_add_u32 s66, s36, 0x80000
	s_addc_u32 s67, s37, 0
	s_add_i32 s68, s57, s3
	v_lshl_add_u64 v[128:129], s[66:67], 0, v[146:147]
	s_mov_b32 m0, s68
	s_nop 0
	global_load_lds_dwordx4 v[128:129], off
	v_lshl_add_u64 v[128:129], s[66:67], 0, v[150:151]
	s_add_i32 m0, s68, 0x2000
	s_nop 0
	global_load_lds_dwordx4 v[128:129], off
	s_waitcnt vmcnt(6)
	s_barrier
	s_setprio 1
	v_mfma_f32_16x16x32_bf16 v[52:55], v[200:203], v[162:165], v[52:55]
	v_mfma_f32_16x16x32_bf16 v[48:51], v[208:211], v[162:165], v[48:51]
	v_mfma_f32_16x16x32_bf16 v[36:39], v[200:203], v[176:179], v[36:39]
	v_mfma_f32_16x16x32_bf16 v[32:35], v[208:211], v[176:179], v[32:35]
	v_mfma_f32_16x16x32_bf16 v[12:15], v[200:203], v[184:187], v[12:15]
	v_mfma_f32_16x16x32_bf16 v[8:11], v[208:211], v[184:187], v[8:11]
	v_mfma_f32_16x16x32_bf16 v[4:7], v[200:203], v[192:195], v[4:7]
	v_mfma_f32_16x16x32_bf16 v[0:3], v[208:211], v[192:195], v[0:3]
	v_mfma_f32_16x16x32_bf16 v[52:55], v[204:207], v[166:169], v[52:55]
	v_mfma_f32_16x16x32_bf16 v[48:51], v[212:215], v[166:169], v[48:51]
	v_mfma_f32_16x16x32_bf16 v[36:39], v[204:207], v[180:183], v[36:39]
	v_mfma_f32_16x16x32_bf16 v[32:35], v[212:215], v[180:183], v[32:35]
	v_mfma_f32_16x16x32_bf16 v[12:15], v[204:207], v[188:191], v[12:15]
	v_mfma_f32_16x16x32_bf16 v[8:11], v[212:215], v[188:191], v[8:11]
	v_mfma_f32_16x16x32_bf16 v[4:7], v[204:207], v[196:199], v[4:7]
	v_mfma_f32_16x16x32_bf16 v[0:3], v[212:215], v[196:199], v[0:3]
	s_setprio 0
	s_add_i32 s66, 0, 0x18000
	v_add_u32_e32 v140, s66, v171
	s_barrier
	ds_read_b128 v[128:131], v140
	ds_read_b128 v[132:135], v140 offset:1024
	ds_read_b128 v[136:139], v140 offset:2048
	ds_read_b128 v[140:143], v140 offset:3072
	s_add_u32 s38, s38, 0x80000
	s_addc_u32 s39, s39, 0
	s_mov_b32 m0, s33
	v_lshl_add_u64 v[200:201], s[38:39], 0, v[144:145]
	ds_read_b128 v[162:165], v174 offset:32768
	ds_read_b128 v[166:169], v174 offset:33792
	ds_read_b128 v[176:179], v174 offset:34816
	ds_read_b128 v[180:183], v174 offset:35840
	ds_read_b128 v[184:187], v174 offset:36864
	ds_read_b128 v[188:191], v174 offset:37888
	ds_read_b128 v[192:195], v174 offset:38912
	ds_read_b128 v[196:199], v174 offset:39936
	global_load_lds_dwordx4 v[200:201], off
	v_lshl_add_u64 v[200:201], s[38:39], 0, v[148:149]
	s_mov_b32 m0, s34
	s_nop 0
	global_load_lds_dwordx4 v[200:201], off
	s_waitcnt lgkmcnt(8)
	s_barrier
	s_waitcnt lgkmcnt(0)
	s_setprio 1
	s_waitcnt lgkmcnt(0)
	v_mfma_f32_16x16x32_bf16 v[124:127], v[128:131], v[162:165], v[124:127]
	v_mfma_f32_16x16x32_bf16 v[120:123], v[136:139], v[162:165], v[120:123]
	v_mfma_f32_16x16x32_bf16 v[108:111], v[128:131], v[176:179], v[108:111]
	v_mfma_f32_16x16x32_bf16 v[104:107], v[136:139], v[176:179], v[104:107]
	v_mfma_f32_16x16x32_bf16 v[92:95], v[128:131], v[184:187], v[92:95]
	v_mfma_f32_16x16x32_bf16 v[88:91], v[136:139], v[184:187], v[88:91]
	v_mfma_f32_16x16x32_bf16 v[84:87], v[128:131], v[192:195], v[84:87]
	v_mfma_f32_16x16x32_bf16 v[80:83], v[136:139], v[192:195], v[80:83]
	v_mfma_f32_16x16x32_bf16 v[124:127], v[132:135], v[166:169], v[124:127]
	v_mfma_f32_16x16x32_bf16 v[120:123], v[140:143], v[166:169], v[120:123]
	v_mfma_f32_16x16x32_bf16 v[108:111], v[132:135], v[180:183], v[108:111]
	v_mfma_f32_16x16x32_bf16 v[104:107], v[140:143], v[180:183], v[104:107]
	v_mfma_f32_16x16x32_bf16 v[92:95], v[132:135], v[188:191], v[92:95]
	v_mfma_f32_16x16x32_bf16 v[88:91], v[140:143], v[188:191], v[88:91]
	v_mfma_f32_16x16x32_bf16 v[84:87], v[132:135], v[196:199], v[84:87]
	v_mfma_f32_16x16x32_bf16 v[80:83], v[140:143], v[196:199], v[80:83]
	s_setprio 0
	s_barrier
	s_add_i32 s38, 0, 0x1c000
	s_add_i32 s39, s66, s3
	v_add_u32_e32 v152, s38, v171
	v_lshl_add_u64 v[158:159], v[158:159], 0, s[8:9]
	s_mov_b32 m0, s39
	ds_read_b128 v[200:203], v152
	ds_read_b128 v[204:207], v152 offset:1024
	ds_read_b128 v[208:211], v152 offset:2048
	ds_read_b128 v[212:215], v152 offset:3072
	global_load_lds_dwordx4 v[158:159], off
	v_lshl_add_u64 v[158:159], v[216:217], 0, s[8:9]
	s_add_i32 m0, s39, 0x2000
	s_nop 0
	global_load_lds_dwordx4 v[158:159], off
	s_barrier
	s_waitcnt lgkmcnt(0)
	s_setprio 1
	s_waitcnt lgkmcnt(0)
	v_mfma_f32_16x16x32_bf16 v[116:119], v[200:203], v[162:165], v[116:119]
	v_mfma_f32_16x16x32_bf16 v[112:115], v[208:211], v[162:165], v[112:115]
	v_mfma_f32_16x16x32_bf16 v[100:103], v[200:203], v[176:179], v[100:103]
	v_mfma_f32_16x16x32_bf16 v[96:99], v[208:211], v[176:179], v[96:99]
	v_mfma_f32_16x16x32_bf16 v[76:79], v[200:203], v[184:187], v[76:79]
	v_mfma_f32_16x16x32_bf16 v[72:75], v[208:211], v[184:187], v[72:75]
	v_mfma_f32_16x16x32_bf16 v[68:71], v[200:203], v[192:195], v[68:71]
	v_mfma_f32_16x16x32_bf16 v[64:67], v[208:211], v[192:195], v[64:67]
	v_mfma_f32_16x16x32_bf16 v[116:119], v[204:207], v[166:169], v[116:119]
	v_mfma_f32_16x16x32_bf16 v[112:115], v[212:215], v[166:169], v[112:115]
	v_mfma_f32_16x16x32_bf16 v[100:103], v[204:207], v[180:183], v[100:103]
	v_mfma_f32_16x16x32_bf16 v[96:99], v[212:215], v[180:183], v[96:99]
	v_mfma_f32_16x16x32_bf16 v[76:79], v[204:207], v[188:191], v[76:79]
	v_mfma_f32_16x16x32_bf16 v[72:75], v[212:215], v[188:191], v[72:75]
	v_mfma_f32_16x16x32_bf16 v[68:71], v[204:207], v[196:199], v[68:71]
	v_mfma_f32_16x16x32_bf16 v[64:67], v[212:215], v[196:199], v[64:67]
	s_setprio 0
	s_mov_b32 m0, s35
	v_lshl_add_u64 v[158:159], v[218:219], 0, s[8:9]
	s_barrier
	ds_read_b128 v[162:165], v174 offset:49152
	ds_read_b128 v[166:169], v174 offset:50176
	ds_read_b128 v[176:179], v174 offset:51200
	ds_read_b128 v[180:183], v174 offset:52224
	ds_read_b128 v[184:187], v174 offset:53248
	ds_read_b128 v[188:191], v174 offset:54272
	ds_read_b128 v[192:195], v174 offset:55296
	ds_read_b128 v[196:199], v174 offset:56320
	global_load_lds_dwordx4 v[158:159], off
	v_lshl_add_u64 v[158:159], v[220:221], 0, s[8:9]
	s_mov_b32 m0, s46
	s_nop 0
	global_load_lds_dwordx4 v[158:159], off
	s_barrier
; #define PG8_STAGE(bufoff, gbase, voff) do { _Pragma("unroll") for (int _i = 0; _i < 2; ++_i) \
;     __builtin_amdgcn_global_load_lds((const unsigned*)((const char*)(gbase) + (voff)[_i]), (LAS unsigned*)(lds + (bufoff) + ldsw + _i * 8192), 16, 0, 0); } while (0)
; #define PG8_MMA(ai, bj, At, Bt) do { __builtin_amdgcn_s_setprio(1); _Pragma("unroll") for (int m = 0; m < 4; ++m) _Pragma("unroll") for (int n = 0; n < 2; ++n) _Pragma("unroll") for (int k = 0; k < 2; ++k) \
;     acc[ai][bj][m][n] = __builtin_amdgcn_mfma_f32_16x16x32_bf16(Bt[n][k], At[m][k], acc[ai][bj][m][n], 0, 0, 0); __builtin_amdgcn_s_setprio(0); } while (0)
; #define PG8_WAIT_V(n) asm volatile("s_waitcnt vmcnt(" #n ")" ::: "memory")
; #define PG8_WAIT_L(n) asm volatile("s_waitcnt lgkmcnt(" #n ")" ::: "memory")
; #define PG8_BAR __builtin_amdgcn_s_barrier()
; #define PG8_SCHED __builtin_amdgcn_sched_barrier(0)
;   DI void operator()(const f32x4 (&acc)[2][2][4][2], const Unit& u, int wr, int wc, int fr, int fq) const {
;     ...
;           f32x4 xv[2][2][2];
; #pragma unroll
;           for (int mm = 0; mm < 2; ++mm) {
;             const int row = rbase + ai * 128 + (mp * 2 + mm) * 16;
;             const float* __restrict__ xs = (row < NPROMPT) ? (P.x_prompt + (size_t)row * 2048) : (P.x_sample + (size_t)(row - NPROMPT) * 2048);
; #pragma unroll
;             for (int bj = 0; bj < 2; ++bj) {
;               const int col = n0 + cbase + bj * 128;
;               xv[mm][bj][0] = *reinterpret_cast<const f32x4*>(xs + col);
;               xv[mm][bj][1] = *reinterpret_cast<const f32x4*>(xs + col + 4);
;             }
; template <class Epi, class Sched>
; DI void gemm_phase(LAS unsigned char* lds, const Sched& S, const Epi& E) {
;     ...
;       PG8_BAR; PG8_WAIT_L(0); PG8_MMA(1, 0, At, B0); PG8_BAR; PG8_SCHED;
;       PG8_STAGE(PG8_SB(1, 1), b3 + hstep, voffB);
;       PG8_WAIT_V(6); PG8_BAR; PG8_MMA(1, 1, At, B1); PG8_BAR;
	s_waitcnt lgkmcnt(0)
	s_setprio 1
	s_waitcnt lgkmcnt(0)
	v_mfma_f32_16x16x32_bf16 v[60:63], v[128:131], v[162:165], v[60:63]
	v_mfma_f32_16x16x32_bf16 v[56:59], v[136:139], v[162:165], v[56:59]
	v_mfma_f32_16x16x32_bf16 v[44:47], v[128:131], v[176:179], v[44:47]
	v_mfma_f32_16x16x32_bf16 v[40:43], v[136:139], v[176:179], v[40:43]
	v_mfma_f32_16x16x32_bf16 v[28:31], v[128:131], v[184:187], v[28:31]
	v_mfma_f32_16x16x32_bf16 v[24:27], v[136:139], v[184:187], v[24:27]
	v_mfma_f32_16x16x32_bf16 v[20:23], v[128:131], v[192:195], v[20:23]
	v_mfma_f32_16x16x32_bf16 v[16:19], v[136:139], v[192:195], v[16:19]
	v_mfma_f32_16x16x32_bf16 v[60:63], v[132:135], v[166:169], v[60:63]
	v_mfma_f32_16x16x32_bf16 v[56:59], v[140:143], v[166:169], v[56:59]
	v_mfma_f32_16x16x32_bf16 v[44:47], v[132:135], v[180:183], v[44:47]
	v_mfma_f32_16x16x32_bf16 v[40:43], v[140:143], v[180:183], v[40:43]
	v_mfma_f32_16x16x32_bf16 v[28:31], v[132:135], v[188:191], v[28:31]
	v_mfma_f32_16x16x32_bf16 v[24:27], v[140:143], v[188:191], v[24:27]
	v_mfma_f32_16x16x32_bf16 v[20:23], v[132:135], v[196:199], v[20:23]
	v_mfma_f32_16x16x32_bf16 v[16:19], v[140:143], v[196:199], v[16:19]
	s_setprio 0
	s_barrier
	s_add_u32 s36, s36, 0x80080
	s_addc_u32 s37, s37, 0
	s_add_i32 s38, s38, s3
	v_lshl_add_u64 v[128:129], s[36:37], 0, v[146:147]
	s_mov_b32 m0, s38
	s_nop 0
	global_load_lds_dwordx4 v[128:129], off
	v_lshl_add_u64 v[128:129], s[36:37], 0, v[150:151]
	s_add_i32 m0, s38, 0x2000
	s_nop 0
	global_load_lds_dwordx4 v[128:129], off
	s_waitcnt vmcnt(6)
	s_barrier
	s_setprio 1
	v_mfma_f32_16x16x32_bf16 v[52:55], v[200:203], v[162:165], v[52:55]
	v_mfma_f32_16x16x32_bf16 v[48:51], v[208:211], v[162:165], v[48:51]
	v_mfma_f32_16x16x32_bf16 v[36:39], v[200:203], v[176:179], v[36:39]
	v_mfma_f32_16x16x32_bf16 v[32:35], v[208:211], v[176:179], v[32:35]
	v_mfma_f32_16x16x32_bf16 v[12:15], v[200:203], v[184:187], v[12:15]
	v_mfma_f32_16x16x32_bf16 v[8:11], v[208:211], v[184:187], v[8:11]
	v_mfma_f32_16x16x32_bf16 v[4:7], v[200:203], v[192:195], v[4:7]
	v_mfma_f32_16x16x32_bf16 v[0:3], v[208:211], v[192:195], v[0:3]
	v_mfma_f32_16x16x32_bf16 v[52:55], v[204:207], v[166:169], v[52:55]
	v_mfma_f32_16x16x32_bf16 v[48:51], v[212:215], v[166:169], v[48:51]
	v_mfma_f32_16x16x32_bf16 v[36:39], v[204:207], v[180:183], v[36:39]
	v_mfma_f32_16x16x32_bf16 v[32:35], v[212:215], v[180:183], v[32:35]
	v_mfma_f32_16x16x32_bf16 v[12:15], v[204:207], v[188:191], v[12:15]
	v_mfma_f32_16x16x32_bf16 v[8:11], v[212:215], v[188:191], v[8:11]
	v_mfma_f32_16x16x32_bf16 v[4:7], v[204:207], v[196:199], v[4:7]
	v_mfma_f32_16x16x32_bf16 v[0:3], v[212:215], v[196:199], v[0:3]
	s_setprio 0
	s_add_i32 s65, s65, 2
	s_add_u32 s30, s30, 0x100
	s_addc_u32 s31, s31, 0
	s_add_u32 s13, s13, 0x100
	s_addc_u32 s25, s25, 0
	s_cmp_gt_u32 s65, 29
	s_barrier
	s_cbranch_scc0 .LBB0_618
	s_lshl_b32 s13, s24, 8
	s_cmp_lt_i32 s13, s47
	s_cselect_b32 s30, s52, s54
	s_cselect_b32 s31, s53, s55
	s_cselect_b32 s25, 0, 0x8000
	s_sub_i32 s25, s13, s25
	s_lshl_b32 s25, s25, 13
	s_lshl_b32 s24, s28, 10
	s_add_u32 s25, s25, s24
	s_add_u32 s30, s30, s25
	s_addc_u32 s31, s31, 0
	s_lshl_b32 s13, s13, 13
	s_add_u32 s13, s13, s24
	s_add_u32 s100, s44, s13
	s_addc_u32 s101, s45, 0
	v_lshlrev_b32_e32 v158, 13, v170
	v_lshl_add_u32 v158, v172, 2, v158
	global_load_dwordx4 v[176:179], v158, s[30:31]
	global_load_dwordx4 v[180:183], v158, s[30:31] offset:16
	global_load_dwordx4 v[184:187], v158, s[30:31] offset:512
	global_load_dwordx4 v[188:191], v158, s[30:31] offset:528
	s_add_u32 s30, s30, 0x20000
	s_addc_u32 s31, s31, 0
	global_load_dwordx4 v[192:195], v158, s[30:31]
	global_load_dwordx4 v[196:199], v158, s[30:31] offset:16
	global_load_dwordx4 v[200:203], v158, s[30:31] offset:512
	global_load_dwordx4 v[204:207], v158, s[30:31] offset:528
	s_add_u32 s30, s30, 0x20000
	s_addc_u32 s31, s31, 0
	global_load_dwordx4 v[208:211], v158, s[30:31]
	global_load_dwordx4 v[212:215], v158, s[30:31] offset:16
	global_load_dwordx4 v[216:219], v158, s[30:31] offset:512
	global_load_dwordx4 v[220:223], v158, s[30:31] offset:528
	s_add_u32 s30, s30, 0x20000
	s_addc_u32 s31, s31, 0
	global_load_dwordx4 v[224:227], v158, s[30:31]
	global_load_dwordx4 v[228:231], v158, s[30:31] offset:16
	global_load_dwordx4 v[232:235], v158, s[30:31] offset:512
	global_load_dwordx4 v[236:239], v158, s[30:31] offset:528
	s_add_u32 s30, s30, 0xa0000
	s_addc_u32 s31, s31, 0
	global_load_dwordx4 v[128:131], v158, s[30:31]
	global_load_dwordx4 v[132:135], v158, s[30:31] offset:16
	global_load_dwordx4 v[136:139], v158, s[30:31] offset:512
	global_load_dwordx4 v[140:143], v158, s[30:31] offset:528
	s_add_u32 s30, s30, 0x20000
	s_addc_u32 s31, s31, 0
	global_load_dwordx4 v[162:165], v158, s[30:31]
	global_load_dwordx4 v[166:169], v158, s[30:31] offset:16
	global_load_dwordx4 v[240:243], v158, s[30:31] offset:512
	global_load_dwordx4 v[244:247], v158, s[30:31] offset:528
	s_waitcnt vmcnt(16)
;   DI void operator()(const f32x4 (&acc)[2][2][4][2], const Unit& u, int wr, int wc, int fr, int fq) const {
;     ...
; #pragma unroll
;           for (int mm = 0; mm < 2; ++mm) {
;             const int row = rbase + ai * 128 + (mp * 2 + mm) * 16;
;             float* __restrict__ od = P.out + O_Y + (size_t)row * 2048;
; #pragma unroll
;             for (int bj = 0; bj < 2; ++bj) {
;               const int col = n0 + cbase + bj * 128;
;               *reinterpret_cast<f32x4*>(od + col) = xv[mm][bj][0] * ALPHA_RES + acc[ai][bj][mp * 2 + mm][0];
;               *reinterpret_cast<f32x4*>(od + col + 4) = xv[mm][bj][1] * ALPHA_RES + acc[ai][bj][mp * 2 + mm][1];
;             }
;           }
	v_pk_fma_f32 v[124:125], v[176:177], s[10:11], v[124:125] op_sel_hi:[1,0,1]
	v_pk_fma_f32 v[126:127], v[178:179], s[10:11], v[126:127] op_sel_hi:[1,0,1]
	v_pk_fma_f32 v[120:121], v[180:181], s[10:11], v[120:121] op_sel_hi:[1,0,1]
	v_pk_fma_f32 v[122:123], v[182:183], s[10:11], v[122:123] op_sel_hi:[1,0,1]
	v_pk_fma_f32 v[116:117], v[184:185], s[10:11], v[116:117] op_sel_hi:[1,0,1]
	v_pk_fma_f32 v[118:119], v[186:187], s[10:11], v[118:119] op_sel_hi:[1,0,1]
	v_pk_fma_f32 v[112:113], v[188:189], s[10:11], v[112:113] op_sel_hi:[1,0,1]
	v_pk_fma_f32 v[114:115], v[190:191], s[10:11], v[114:115] op_sel_hi:[1,0,1]
	v_pk_fma_f32 v[108:109], v[192:193], s[10:11], v[108:109] op_sel_hi:[1,0,1]
	v_pk_fma_f32 v[110:111], v[194:195], s[10:11], v[110:111] op_sel_hi:[1,0,1]
	v_pk_fma_f32 v[104:105], v[196:197], s[10:11], v[104:105] op_sel_hi:[1,0,1]
	v_pk_fma_f32 v[106:107], v[198:199], s[10:11], v[106:107] op_sel_hi:[1,0,1]
	v_pk_fma_f32 v[100:101], v[200:201], s[10:11], v[100:101] op_sel_hi:[1,0,1]
	v_pk_fma_f32 v[102:103], v[202:203], s[10:11], v[102:103] op_sel_hi:[1,0,1]
	v_pk_fma_f32 v[96:97], v[204:205], s[10:11], v[96:97] op_sel_hi:[1,0,1]
	v_pk_fma_f32 v[98:99], v[206:207], s[10:11], v[98:99] op_sel_hi:[1,0,1]
	global_store_dwordx4 v158, v[124:127], s[100:101]
	global_store_dwordx4 v158, v[120:123], s[100:101] offset:16
	global_store_dwordx4 v158, v[116:119], s[100:101] offset:512
	global_store_dwordx4 v158, v[112:115], s[100:101] offset:528
	s_add_u32 s100, s100, 0x20000
	s_addc_u32 s101, s101, 0
	global_store_dwordx4 v158, v[108:111], s[100:101]
	global_store_dwordx4 v158, v[104:107], s[100:101] offset:16
	global_store_dwordx4 v158, v[100:103], s[100:101] offset:512
	global_store_dwordx4 v158, v[96:99], s[100:101] offset:528
	s_add_u32 s30, s30, 0x20000
	s_addc_u32 s31, s31, 0
	global_load_dwordx4 v[176:179], v158, s[30:31]
	global_load_dwordx4 v[180:183], v158, s[30:31] offset:16
	global_load_dwordx4 v[184:187], v158, s[30:31] offset:512
	global_load_dwordx4 v[188:191], v158, s[30:31] offset:528
	s_add_u32 s30, s30, 0x20000
	s_addc_u32 s31, s31, 0
	global_load_dwordx4 v[192:195], v158, s[30:31]
	global_load_dwordx4 v[196:199], v158, s[30:31] offset:16
	global_load_dwordx4 v[200:203], v158, s[30:31] offset:512
	global_load_dwordx4 v[204:207], v158, s[30:31] offset:528
	s_waitcnt vmcnt(24)
	v_pk_fma_f32 v[92:93], v[208:209], s[10:11], v[92:93] op_sel_hi:[1,0,1]
	v_pk_fma_f32 v[94:95], v[210:211], s[10:11], v[94:95] op_sel_hi:[1,0,1]
	v_pk_fma_f32 v[88:89], v[212:213], s[10:11], v[88:89] op_sel_hi:[1,0,1]
	v_pk_fma_f32 v[90:91], v[214:215], s[10:11], v[90:91] op_sel_hi:[1,0,1]
	v_pk_fma_f32 v[76:77], v[216:217], s[10:11], v[76:77] op_sel_hi:[1,0,1]
	v_pk_fma_f32 v[78:79], v[218:219], s[10:11], v[78:79] op_sel_hi:[1,0,1]
	v_pk_fma_f32 v[72:73], v[220:221], s[10:11], v[72:73] op_sel_hi:[1,0,1]
	v_pk_fma_f32 v[74:75], v[222:223], s[10:11], v[74:75] op_sel_hi:[1,0,1]
	v_pk_fma_f32 v[84:85], v[224:225], s[10:11], v[84:85] op_sel_hi:[1,0,1]
	v_pk_fma_f32 v[86:87], v[226:227], s[10:11], v[86:87] op_sel_hi:[1,0,1]
	v_pk_fma_f32 v[80:81], v[228:229], s[10:11], v[80:81] op_sel_hi:[1,0,1]
	v_pk_fma_f32 v[82:83], v[230:231], s[10:11], v[82:83] op_sel_hi:[1,0,1]
	v_pk_fma_f32 v[68:69], v[232:233], s[10:11], v[68:69] op_sel_hi:[1,0,1]
	v_pk_fma_f32 v[70:71], v[234:235], s[10:11], v[70:71] op_sel_hi:[1,0,1]
	v_pk_fma_f32 v[64:65], v[236:237], s[10:11], v[64:65] op_sel_hi:[1,0,1]
	v_pk_fma_f32 v[66:67], v[238:239], s[10:11], v[66:67] op_sel_hi:[1,0,1]
	s_add_u32 s100, s100, 0x20000
	s_addc_u32 s101, s101, 0
	global_store_dwordx4 v158, v[92:95], s[100:101]
	global_store_dwordx4 v158, v[88:91], s[100:101] offset:16
	global_store_dwordx4 v158, v[76:79], s[100:101] offset:512
	global_store_dwordx4 v158, v[72:75], s[100:101] offset:528
	s_add_u32 s100, s100, 0x20000
	s_addc_u32 s101, s101, 0
	global_store_dwordx4 v158, v[84:87], s[100:101]
	global_store_dwordx4 v158, v[80:83], s[100:101] offset:16
	global_store_dwordx4 v158, v[68:71], s[100:101] offset:512
	global_store_dwordx4 v158, v[64:67], s[100:101] offset:528
	s_waitcnt vmcnt(24)
;   DI void done(const Unit& u, int ui, bool has_next, int lane) const {
;     if (handoff && u.kind == 2 && ui == 3 && has_next) {
;       __builtin_amdgcn_fence(__ATOMIC_RELEASE, "agent");
;       if (lane == 0) __hip_atomic_fetch_add(p->lnready, 1, __ATOMIC_RELAXED, __HIP_MEMORY_SCOPE_AGENT);
;     }
;   DI void operator()(const f32x4 (&acc)[2][2][4][2], const Unit& u, int wr, int wc, int fr, int fq) const {
;     ...
; #pragma unroll
;           for (int mm = 0; mm < 2; ++mm) {
;             const int row = rbase + ai * 128 + (mp * 2 + mm) * 16;
;             float* __restrict__ od = P.out + O_Y + (size_t)row * 2048;
; #pragma unroll
;             for (int bj = 0; bj < 2; ++bj) {
;               const int col = n0 + cbase + bj * 128;
;               *reinterpret_cast<f32x4*>(od + col) = xv[mm][bj][0] * ALPHA_RES + acc[ai][bj][mp * 2 + mm][0];
;               *reinterpret_cast<f32x4*>(od + col + 4) = xv[mm][bj][1] * ALPHA_RES + acc[ai][bj][mp * 2 + mm][1];
;             }
;           }
	v_pk_fma_f32 v[60:61], v[128:129], s[10:11], v[60:61] op_sel_hi:[1,0,1]
	v_pk_fma_f32 v[62:63], v[130:131], s[10:11], v[62:63] op_sel_hi:[1,0,1]
	v_pk_fma_f32 v[56:57], v[132:133], s[10:11], v[56:57] op_sel_hi:[1,0,1]
	v_pk_fma_f32 v[58:59], v[134:135], s[10:11], v[58:59] op_sel_hi:[1,0,1]
	v_pk_fma_f32 v[52:53], v[136:137], s[10:11], v[52:53] op_sel_hi:[1,0,1]
	v_pk_fma_f32 v[54:55], v[138:139], s[10:11], v[54:55] op_sel_hi:[1,0,1]
	v_pk_fma_f32 v[48:49], v[140:141], s[10:11], v[48:49] op_sel_hi:[1,0,1]
	v_pk_fma_f32 v[50:51], v[142:143], s[10:11], v[50:51] op_sel_hi:[1,0,1]
	v_pk_fma_f32 v[44:45], v[162:163], s[10:11], v[44:45] op_sel_hi:[1,0,1]
	v_pk_fma_f32 v[46:47], v[164:165], s[10:11], v[46:47] op_sel_hi:[1,0,1]
	v_pk_fma_f32 v[40:41], v[166:167], s[10:11], v[40:41] op_sel_hi:[1,0,1]
	v_pk_fma_f32 v[42:43], v[168:169], s[10:11], v[42:43] op_sel_hi:[1,0,1]
	v_pk_fma_f32 v[36:37], v[240:241], s[10:11], v[36:37] op_sel_hi:[1,0,1]
	v_pk_fma_f32 v[38:39], v[242:243], s[10:11], v[38:39] op_sel_hi:[1,0,1]
	v_pk_fma_f32 v[32:33], v[244:245], s[10:11], v[32:33] op_sel_hi:[1,0,1]
	v_pk_fma_f32 v[34:35], v[246:247], s[10:11], v[34:35] op_sel_hi:[1,0,1]
	s_add_u32 s100, s100, 0xa0000
	s_addc_u32 s101, s101, 0
	global_store_dwordx4 v158, v[60:63], s[100:101]
	global_store_dwordx4 v158, v[56:59], s[100:101] offset:16
	global_store_dwordx4 v158, v[52:55], s[100:101] offset:512
	global_store_dwordx4 v158, v[48:51], s[100:101] offset:528
	s_add_u32 s100, s100, 0x20000
	s_addc_u32 s101, s101, 0
	global_store_dwordx4 v158, v[44:47], s[100:101]
	global_store_dwordx4 v158, v[40:43], s[100:101] offset:16
	global_store_dwordx4 v158, v[36:39], s[100:101] offset:512
	global_store_dwordx4 v158, v[32:35], s[100:101] offset:528
	s_waitcnt vmcnt(16)
	v_pk_fma_f32 v[28:29], v[176:177], s[10:11], v[28:29] op_sel_hi:[1,0,1]
	v_pk_fma_f32 v[30:31], v[178:179], s[10:11], v[30:31] op_sel_hi:[1,0,1]
	v_pk_fma_f32 v[24:25], v[180:181], s[10:11], v[24:25] op_sel_hi:[1,0,1]
	v_pk_fma_f32 v[26:27], v[182:183], s[10:11], v[26:27] op_sel_hi:[1,0,1]
	v_pk_fma_f32 v[12:13], v[184:185], s[10:11], v[12:13] op_sel_hi:[1,0,1]
	v_pk_fma_f32 v[14:15], v[186:187], s[10:11], v[14:15] op_sel_hi:[1,0,1]
	v_pk_fma_f32 v[8:9], v[188:189], s[10:11], v[8:9] op_sel_hi:[1,0,1]
	v_pk_fma_f32 v[10:11], v[190:191], s[10:11], v[10:11] op_sel_hi:[1,0,1]
	v_pk_fma_f32 v[20:21], v[192:193], s[10:11], v[20:21] op_sel_hi:[1,0,1]
	v_pk_fma_f32 v[22:23], v[194:195], s[10:11], v[22:23] op_sel_hi:[1,0,1]
	v_pk_fma_f32 v[16:17], v[196:197], s[10:11], v[16:17] op_sel_hi:[1,0,1]
	v_pk_fma_f32 v[18:19], v[198:199], s[10:11], v[18:19] op_sel_hi:[1,0,1]
	v_pk_fma_f32 v[4:5], v[200:201], s[10:11], v[4:5] op_sel_hi:[1,0,1]
	v_pk_fma_f32 v[6:7], v[202:203], s[10:11], v[6:7] op_sel_hi:[1,0,1]
	v_pk_fma_f32 v[0:1], v[204:205], s[10:11], v[0:1] op_sel_hi:[1,0,1]
	v_pk_fma_f32 v[2:3], v[206:207], s[10:11], v[2:3] op_sel_hi:[1,0,1]
	s_add_u32 s100, s100, 0x20000
	s_addc_u32 s101, s101, 0
	global_store_dwordx4 v158, v[28:31], s[100:101]
	global_store_dwordx4 v158, v[24:27], s[100:101] offset:16
	global_store_dwordx4 v158, v[12:15], s[100:101] offset:512
	global_store_dwordx4 v158, v[8:11], s[100:101] offset:528
	s_add_u32 s100, s100, 0x20000
	s_addc_u32 s101, s101, 0
	global_store_dwordx4 v158, v[20:23], s[100:101]
	global_store_dwordx4 v158, v[16:19], s[100:101] offset:16
	global_store_dwordx4 v158, v[4:7], s[100:101] offset:512
	global_store_dwordx4 v158, v[0:3], s[100:101] offset:528
	s_cmp_eq_u32 s64, 3
	v_readlane_b32 s30, v254, 4
	s_cselect_b64 s[24:25], -1, 0
	v_readlane_b32 s31, v254, 5
	s_and_b64 s[24:25], s[30:31], s[24:25]
	s_and_b64 s[22:23], s[24:25], s[22:23]
	s_andn2_b64 vcc, exec, s[22:23]
	s_cbranch_vccnz .LBB0_610
	buffer_wbl2 sc1
	s_waitcnt vmcnt(0) lgkmcnt(0)
	s_and_saveexec_b64 s[22:23], s[0:1]
	s_cbranch_execz .LBB0_609
	s_mov_b64 s[24:25], exec
	v_mbcnt_lo_u32_b32 v0, s24, 0
	v_mbcnt_hi_u32_b32 v0, s25, v0
	v_cmp_eq_u32_e32 vcc, 0, v0
	s_and_b64 s[30:31], exec, vcc
	s_mov_b64 exec, s[30:31]
	s_cbranch_execz .LBB0_609
	s_bcnt1_i32_b64 s13, s[24:25]
	v_mov_b32_e32 v0, s13
	global_atomic_add v153, v0, s[50:51]
	s_branch .LBB0_609
